# W1 (full batch) GEMM: the tile's additive vector is fetched at the top of the tile, the epilogue no longer starts by draining the next tile's staged loads
# speedup vs baseline: 1.0271x; 1.0011x over previous
.LBB0_556:
	s_ashr_i32 s98, s24, 3
	s_lshl_b32 s98, s98, 14
	s_add_u32 s98, s1, s98
	s_addc_u32 s99, s31, 0
	v_lshl_add_u32 v226, s42, 8, v170
	v_lshlrev_b32_e32 v226, 2, v226
	global_load_dwordx4 v[230:233], v226, s[98:99] offset:16
	global_load_dwordx4 v[236:239], v226, s[98:99]
	global_load_dwordx4 v[240:243], v226, s[98:99] offset:528
	global_load_dwordx4 v[226:229], v226, s[98:99] offset:512
	s_add_i32 s37, s22, 1
	s_mul_i32 s15, s37, s97
	s_mul_hi_u32 s19, s37, s96
	s_add_i32 s19, s19, s15
	s_mul_i32 s15, s37, s96
	s_add_u32 s20, s15, s2
	s_addc_u32 s21, s19, s3
	v_cmp_gt_i64_e32 vcc, s[20:21], v[156:157]
	v_cmp_lt_i64_e64 s[38:39], s[20:21], v[234:235]
	s_cbranch_vccnz .LBB0_558
	s_ashr_i32 s14, s20, 31
	s_lshr_b32 s14, s14, 29
	s_add_i32 s14, s20, s14
	s_ashr_i32 s15, s14, 3
	s_and_b32 s14, s14, -8
	s_sub_i32 s14, s20, s14
	v_mov_b32_e32 v0, s14
	v_alignbit_b32 v0, s74, v0, 31
	s_nop 0
	v_readfirstlane_b32 s18, v0
	s_mul_i32 s14, s18, s14
	s_add_i32 s14, s14, s15
	s_ashr_i32 s15, s14, 31
	s_lshr_b32 s15, s15, 26
	s_add_i32 s15, s14, s15
	s_ashr_i32 s18, s15, 6
	s_lshl_b32 s18, s18, 2
	s_sub_i32 s19, 0x80, s18
	s_min_i32 s19, s19, 4
	s_abs_i32 s20, s19
	v_cvt_f32_u32_e32 v0, s20
	s_sub_i32 s23, 0, s20
	s_andn2_b32 s15, s15, 63
	s_sub_i32 s15, s14, s15
	v_rcp_iflag_f32_e32 v0, v0
	s_abs_i32 s14, s15
	s_xor_b32 s21, s15, s19
	s_ashr_i32 s21, s21, 31
	v_mul_f32_e32 v0, 0x4f7ffffe, v0
	v_cvt_u32_f32_e32 v0, v0
	s_nop 0
	v_readfirstlane_b32 s40, v0
	s_mul_i32 s23, s23, s40
	s_mul_hi_u32 s23, s40, s23
	s_add_i32 s40, s40, s23
	s_mul_hi_u32 s23, s14, s40
	s_mul_i32 s40, s23, s20
	s_sub_i32 s14, s14, s40
	s_add_i32 s41, s23, 1
	s_sub_i32 s40, s14, s20
	s_cmp_ge_u32 s14, s20
	s_cselect_b32 s23, s41, s23
	s_cselect_b32 s14, s40, s14
	s_add_i32 s40, s23, 1
	s_cmp_ge_u32 s14, s20
	s_cselect_b32 s14, s40, s23
	s_xor_b32 s14, s14, s21
	s_sub_i32 s14, s14, s21
	s_mul_i32 s19, s14, s19
	s_sub_i32 s15, s15, s19
	s_add_i32 s18, s15, s18

.LBB0_562:
	s_mov_b64 s[44:45], 0
	s_mov_b64 s[60:61], 0
	s_mov_b64 s[60:61], 0
	s_add_u32 s15, s1, s60
	s_addc_u32 s19, s31, s61
	s_ashr_i32 s60, s24, 3
	s_ashr_i32 s61, s60, 31
	v_lshl_add_u32 v164, s42, 8, v170
	s_lshl_b64 s[42:43], s[60:61], 14
	s_add_u32 s42, s15, s42
	s_addc_u32 s43, s19, s43
	v_ashrrev_i32_e32 v165, 31, v164
	v_lshl_add_u64 v[116:117], v[164:165], 2, s[42:43]
	v_mov_b64_e32 v[120:121], v[230:231]
	v_mov_b64_e32 v[122:123], v[232:233]
	v_mov_b64_e32 v[124:125], v[236:237]
	v_mov_b64_e32 v[126:127], v[238:239]
	v_mov_b64_e32 v[112:113], v[240:241]
	v_mov_b64_e32 v[114:115], v[242:243]
	s_nop 0
	v_mov_b64_e32 v[116:117], v[226:227]
	v_mov_b64_e32 v[118:119], v[228:229]
	s_add_u32 s42, s6, s44
	s_addc_u32 s43, s72, s45
	s_sub_i32 s15, s22, s24
	s_lshl_b32 s15, s15, 10
	s_add_i32 s15, s15, 0
	v_lshl_add_u32 v166, s24, 8, v168
	s_add_i32 s15, s15, 0x20000
	v_lshl_add_u32 v154, v166, 2, s15
	ds_read_b32 v172, v154
	v_ashrrev_i32_e32 v167, 31, v166
	v_lshl_add_u64 v[164:165], v[164:165], 1, s[42:43]
	v_lshlrev_b64 v[174:175], 13, v[166:167]
	v_lshl_add_u64 v[174:175], v[164:165], 0, v[174:175]
	s_mov_b64 s[22:23], -1
	s_andn2_b64 vcc, exec, s[38:39]
	s_waitcnt lgkmcnt(0)
	v_pk_fma_f32 v[136:137], v[136:137], v[172:173], v[120:121] op_sel_hi:[1,0,1]
	v_pk_fma_f32 v[142:143], v[142:143], v[172:173], v[126:127] op_sel_hi:[1,0,1]
	v_pk_fma_f32 v[140:141], v[140:141], v[172:173], v[124:125] op_sel_hi:[1,0,1]
	v_pk_fma_f32 v[138:139], v[138:139], v[172:173], v[122:123] op_sel_hi:[1,0,1]
	v_max_f32_e32 v136, 0, v136
	v_max_f32_e32 v137, 0, v137
	v_max_f32_e32 v140, 0, v140
	v_max_f32_e32 v141, 0, v141
	v_pk_mul_f32 v[176:177], v[136:137], v[136:137]
	v_max_f32_e32 v136, 0, v142
	v_max_f32_e32 v138, 0, v138
	v_max_f32_e32 v137, 0, v143
	v_max_f32_e32 v139, 0, v139
	v_pk_mul_f32 v[140:141], v[140:141], v[140:141]
	v_pk_mul_f32 v[142:143], v[136:137], v[136:137]
	v_pk_mul_f32 v[178:179], v[138:139], v[138:139]
	v_pk_fma_f32 v[128:129], v[128:129], v[172:173], v[112:113] op_sel_hi:[1,0,1]
	v_cvt_pk_bf16_f32 v136, v140, v141
	v_cvt_pk_bf16_f32 v137, v142, v143
	v_cvt_pk_bf16_f32 v138, v176, v177
	v_cvt_pk_bf16_f32 v139, v178, v179
	v_pk_fma_f32 v[134:135], v[134:135], v[172:173], v[118:119] op_sel_hi:[1,0,1]
	v_pk_fma_f32 v[132:133], v[132:133], v[172:173], v[116:117] op_sel_hi:[1,0,1]
	v_pk_fma_f32 v[130:131], v[130:131], v[172:173], v[114:115] op_sel_hi:[1,0,1]
	v_max_f32_e32 v128, 0, v128
	v_max_f32_e32 v129, 0, v129
	global_store_dwordx4 v[174:175], v[136:139], off
	v_max_f32_e32 v132, 0, v132
	v_max_f32_e32 v133, 0, v133
	v_pk_mul_f32 v[136:137], v[128:129], v[128:129]
	v_max_f32_e32 v128, 0, v134
	v_max_f32_e32 v130, 0, v130
	v_max_f32_e32 v129, 0, v135
	v_max_f32_e32 v131, 0, v131
	v_pk_mul_f32 v[132:133], v[132:133], v[132:133]
	v_pk_mul_f32 v[134:135], v[128:129], v[128:129]
	v_pk_mul_f32 v[138:139], v[130:131], v[130:131]
	v_cvt_pk_bf16_f32 v128, v132, v133
	v_cvt_pk_bf16_f32 v129, v134, v135
	v_cvt_pk_bf16_f32 v130, v136, v137
	v_cvt_pk_bf16_f32 v131, v138, v139
	global_store_dwordx4 v[174:175], v[128:131], off offset:256
	s_nop 1
	v_or_b32_e32 v128, 16, v166
	v_lshl_add_u32 v129, v128, 2, s15
	ds_read_b32 v130, v129
	v_ashrrev_i32_e32 v129, 31, v128
	v_lshlrev_b64 v[128:129], 13, v[128:129]
	v_lshl_add_u64 v[128:129], v[164:165], 0, v[128:129]
	s_waitcnt lgkmcnt(0)
	v_pk_fma_f32 v[104:105], v[104:105], v[130:131], v[120:121] op_sel_hi:[1,0,1]
	v_pk_fma_f32 v[110:111], v[110:111], v[130:131], v[126:127] op_sel_hi:[1,0,1]
	v_pk_fma_f32 v[108:109], v[108:109], v[130:131], v[124:125] op_sel_hi:[1,0,1]
	v_pk_fma_f32 v[106:107], v[106:107], v[130:131], v[122:123] op_sel_hi:[1,0,1]
	v_max_f32_e32 v104, 0, v104
	v_max_f32_e32 v105, 0, v105
	v_max_f32_e32 v108, 0, v108
	v_max_f32_e32 v109, 0, v109
	v_pk_mul_f32 v[132:133], v[104:105], v[104:105]
	v_max_f32_e32 v104, 0, v110
	v_max_f32_e32 v106, 0, v106
	v_max_f32_e32 v105, 0, v111
	v_max_f32_e32 v107, 0, v107
	v_pk_mul_f32 v[108:109], v[108:109], v[108:109]
	v_pk_mul_f32 v[110:111], v[104:105], v[104:105]
	v_pk_mul_f32 v[134:135], v[106:107], v[106:107]
	v_pk_fma_f32 v[96:97], v[96:97], v[130:131], v[112:113] op_sel_hi:[1,0,1]
	v_cvt_pk_bf16_f32 v104, v108, v109
	v_cvt_pk_bf16_f32 v105, v110, v111
	v_cvt_pk_bf16_f32 v106, v132, v133
	v_cvt_pk_bf16_f32 v107, v134, v135
	v_pk_fma_f32 v[102:103], v[102:103], v[130:131], v[118:119] op_sel_hi:[1,0,1]
	v_pk_fma_f32 v[100:101], v[100:101], v[130:131], v[116:117] op_sel_hi:[1,0,1]
	v_pk_fma_f32 v[98:99], v[98:99], v[130:131], v[114:115] op_sel_hi:[1,0,1]
	v_max_f32_e32 v96, 0, v96
	v_max_f32_e32 v97, 0, v97
	global_store_dwordx4 v[128:129], v[104:107], off
	v_max_f32_e32 v100, 0, v100
	v_max_f32_e32 v101, 0, v101
	v_pk_mul_f32 v[104:105], v[96:97], v[96:97]
	v_max_f32_e32 v96, 0, v102
	v_max_f32_e32 v98, 0, v98
	v_max_f32_e32 v97, 0, v103
	v_max_f32_e32 v99, 0, v99
	v_pk_mul_f32 v[100:101], v[100:101], v[100:101]
	v_pk_mul_f32 v[102:103], v[96:97], v[96:97]
	v_pk_mul_f32 v[106:107], v[98:99], v[98:99]
	v_cvt_pk_bf16_f32 v96, v100, v101
	v_cvt_pk_bf16_f32 v97, v102, v103
	v_cvt_pk_bf16_f32 v98, v104, v105
	v_cvt_pk_bf16_f32 v99, v106, v107
	global_store_dwordx4 v[128:129], v[96:99], off offset:256
	s_nop 1
	v_or_b32_e32 v96, 32, v166
	v_lshl_add_u32 v97, v96, 2, s15
	ds_read_b32 v98, v97
	v_ashrrev_i32_e32 v97, 31, v96
	v_lshlrev_b64 v[96:97], 13, v[96:97]
	v_lshl_add_u64 v[96:97], v[164:165], 0, v[96:97]
	s_waitcnt lgkmcnt(0)
	v_pk_fma_f32 v[88:89], v[88:89], v[98:99], v[120:121] op_sel_hi:[1,0,1]
	v_pk_fma_f32 v[94:95], v[94:95], v[98:99], v[126:127] op_sel_hi:[1,0,1]
	v_pk_fma_f32 v[92:93], v[92:93], v[98:99], v[124:125] op_sel_hi:[1,0,1]
	v_pk_fma_f32 v[90:91], v[90:91], v[98:99], v[122:123] op_sel_hi:[1,0,1]
	v_max_f32_e32 v88, 0, v88
	v_max_f32_e32 v89, 0, v89
	v_max_f32_e32 v92, 0, v92
	v_max_f32_e32 v93, 0, v93
	v_pk_mul_f32 v[100:101], v[88:89], v[88:89]
	v_max_f32_e32 v88, 0, v94
	v_max_f32_e32 v90, 0, v90
	v_max_f32_e32 v89, 0, v95
	v_max_f32_e32 v91, 0, v91
	v_pk_mul_f32 v[92:93], v[92:93], v[92:93]
	v_pk_mul_f32 v[94:95], v[88:89], v[88:89]
	v_pk_mul_f32 v[102:103], v[90:91], v[90:91]
	v_pk_fma_f32 v[80:81], v[80:81], v[98:99], v[112:113] op_sel_hi:[1,0,1]
	v_cvt_pk_bf16_f32 v88, v92, v93
	v_cvt_pk_bf16_f32 v89, v94, v95
	v_cvt_pk_bf16_f32 v90, v100, v101
	v_cvt_pk_bf16_f32 v91, v102, v103
	v_pk_fma_f32 v[86:87], v[86:87], v[98:99], v[118:119] op_sel_hi:[1,0,1]
	v_pk_fma_f32 v[84:85], v[84:85], v[98:99], v[116:117] op_sel_hi:[1,0,1]
	v_pk_fma_f32 v[82:83], v[82:83], v[98:99], v[114:115] op_sel_hi:[1,0,1]
	v_max_f32_e32 v80, 0, v80
	v_max_f32_e32 v81, 0, v81
	global_store_dwordx4 v[96:97], v[88:91], off
	v_max_f32_e32 v84, 0, v84
	v_max_f32_e32 v85, 0, v85
	v_pk_mul_f32 v[88:89], v[80:81], v[80:81]
	v_max_f32_e32 v80, 0, v86
	v_max_f32_e32 v82, 0, v82
	v_max_f32_e32 v81, 0, v87
	v_max_f32_e32 v83, 0, v83
	v_pk_mul_f32 v[84:85], v[84:85], v[84:85]
	v_pk_mul_f32 v[86:87], v[80:81], v[80:81]
	v_pk_mul_f32 v[90:91], v[82:83], v[82:83]
	v_cvt_pk_bf16_f32 v80, v84, v85
	v_cvt_pk_bf16_f32 v81, v86, v87
	v_cvt_pk_bf16_f32 v82, v88, v89
	v_cvt_pk_bf16_f32 v83, v90, v91
	global_store_dwordx4 v[96:97], v[80:83], off offset:256
	s_nop 1
	v_or_b32_e32 v80, 48, v166
	v_lshl_add_u32 v81, v80, 2, s15
	ds_read_b32 v82, v81
	v_ashrrev_i32_e32 v81, 31, v80
	v_lshlrev_b64 v[80:81], 13, v[80:81]
	v_lshl_add_u64 v[80:81], v[164:165], 0, v[80:81]
	s_waitcnt lgkmcnt(0)
	v_pk_fma_f32 v[72:73], v[72:73], v[82:83], v[120:121] op_sel_hi:[1,0,1]
	v_pk_fma_f32 v[78:79], v[78:79], v[82:83], v[126:127] op_sel_hi:[1,0,1]
	v_pk_fma_f32 v[76:77], v[76:77], v[82:83], v[124:125] op_sel_hi:[1,0,1]
	v_pk_fma_f32 v[74:75], v[74:75], v[82:83], v[122:123] op_sel_hi:[1,0,1]
	v_max_f32_e32 v72, 0, v72
	v_max_f32_e32 v73, 0, v73
	v_max_f32_e32 v76, 0, v76
	v_max_f32_e32 v77, 0, v77
	v_pk_mul_f32 v[84:85], v[72:73], v[72:73]
	v_max_f32_e32 v72, 0, v78
	v_max_f32_e32 v74, 0, v74
	v_max_f32_e32 v73, 0, v79
	v_max_f32_e32 v75, 0, v75
	v_pk_mul_f32 v[76:77], v[76:77], v[76:77]
	v_pk_mul_f32 v[78:79], v[72:73], v[72:73]
	v_pk_mul_f32 v[86:87], v[74:75], v[74:75]
	v_pk_fma_f32 v[64:65], v[64:65], v[82:83], v[112:113] op_sel_hi:[1,0,1]
	v_cvt_pk_bf16_f32 v72, v76, v77
	v_cvt_pk_bf16_f32 v73, v78, v79
	v_cvt_pk_bf16_f32 v74, v84, v85
	v_cvt_pk_bf16_f32 v75, v86, v87
	v_pk_fma_f32 v[70:71], v[70:71], v[82:83], v[118:119] op_sel_hi:[1,0,1]
	v_pk_fma_f32 v[68:69], v[68:69], v[82:83], v[116:117] op_sel_hi:[1,0,1]
	v_pk_fma_f32 v[66:67], v[66:67], v[82:83], v[114:115] op_sel_hi:[1,0,1]
	v_max_f32_e32 v64, 0, v64
	v_max_f32_e32 v65, 0, v65
	global_store_dwordx4 v[80:81], v[72:75], off
	v_max_f32_e32 v68, 0, v68
	v_max_f32_e32 v69, 0, v69
	v_pk_mul_f32 v[72:73], v[64:65], v[64:65]
	v_max_f32_e32 v64, 0, v70
	v_max_f32_e32 v66, 0, v66
	v_max_f32_e32 v65, 0, v71
	v_max_f32_e32 v67, 0, v67
	v_pk_mul_f32 v[68:69], v[68:69], v[68:69]
	v_pk_mul_f32 v[70:71], v[64:65], v[64:65]
	v_pk_mul_f32 v[74:75], v[66:67], v[66:67]
	v_cvt_pk_bf16_f32 v64, v68, v69
	v_cvt_pk_bf16_f32 v65, v70, v71
	v_cvt_pk_bf16_f32 v66, v72, v73
	v_cvt_pk_bf16_f32 v67, v74, v75
	global_store_dwordx4 v[80:81], v[64:67], off offset:256
	s_nop 1
	v_add_u32_e32 v64, 0x80, v166
	v_lshl_add_u32 v65, v64, 2, s15
	ds_read_b32 v66, v65
	v_ashrrev_i32_e32 v65, 31, v64
	v_lshlrev_b64 v[64:65], 13, v[64:65]
	v_lshl_add_u64 v[64:65], v[164:165], 0, v[64:65]
	s_waitcnt lgkmcnt(0)
	v_pk_fma_f32 v[56:57], v[56:57], v[66:67], v[120:121] op_sel_hi:[1,0,1]
	v_pk_fma_f32 v[62:63], v[62:63], v[66:67], v[126:127] op_sel_hi:[1,0,1]
	v_pk_fma_f32 v[60:61], v[60:61], v[66:67], v[124:125] op_sel_hi:[1,0,1]
	v_pk_fma_f32 v[58:59], v[58:59], v[66:67], v[122:123] op_sel_hi:[1,0,1]
	v_max_f32_e32 v56, 0, v56
	v_max_f32_e32 v57, 0, v57
	v_max_f32_e32 v60, 0, v60
	v_max_f32_e32 v61, 0, v61
	v_pk_mul_f32 v[68:69], v[56:57], v[56:57]
	v_max_f32_e32 v56, 0, v62
	v_max_f32_e32 v58, 0, v58
	v_max_f32_e32 v57, 0, v63
	v_max_f32_e32 v59, 0, v59
	v_pk_mul_f32 v[60:61], v[60:61], v[60:61]
	v_pk_mul_f32 v[62:63], v[56:57], v[56:57]
	v_pk_mul_f32 v[70:71], v[58:59], v[58:59]
	v_pk_fma_f32 v[48:49], v[48:49], v[66:67], v[112:113] op_sel_hi:[1,0,1]
	v_cvt_pk_bf16_f32 v56, v60, v61
	v_cvt_pk_bf16_f32 v57, v62, v63
	v_cvt_pk_bf16_f32 v58, v68, v69
	v_cvt_pk_bf16_f32 v59, v70, v71
	v_pk_fma_f32 v[54:55], v[54:55], v[66:67], v[118:119] op_sel_hi:[1,0,1]
	v_pk_fma_f32 v[52:53], v[52:53], v[66:67], v[116:117] op_sel_hi:[1,0,1]
	v_pk_fma_f32 v[50:51], v[50:51], v[66:67], v[114:115] op_sel_hi:[1,0,1]
	v_max_f32_e32 v48, 0, v48
	v_max_f32_e32 v49, 0, v49
	global_store_dwordx4 v[64:65], v[56:59], off
	v_max_f32_e32 v52, 0, v52
	v_max_f32_e32 v53, 0, v53
	v_pk_mul_f32 v[56:57], v[48:49], v[48:49]
	v_max_f32_e32 v48, 0, v54
	v_max_f32_e32 v50, 0, v50
	v_max_f32_e32 v49, 0, v55
	v_max_f32_e32 v51, 0, v51
	v_pk_mul_f32 v[52:53], v[52:53], v[52:53]
	v_pk_mul_f32 v[54:55], v[48:49], v[48:49]
	v_pk_mul_f32 v[58:59], v[50:51], v[50:51]
	v_cvt_pk_bf16_f32 v48, v52, v53
	v_cvt_pk_bf16_f32 v49, v54, v55
	v_cvt_pk_bf16_f32 v50, v56, v57
	v_cvt_pk_bf16_f32 v51, v58, v59
	global_store_dwordx4 v[64:65], v[48:51], off offset:256
	s_nop 1
	v_add_u32_e32 v48, 0x90, v166
	v_lshl_add_u32 v49, v48, 2, s15
	ds_read_b32 v50, v49
	v_ashrrev_i32_e32 v49, 31, v48
	v_lshlrev_b64 v[48:49], 13, v[48:49]
	v_lshl_add_u64 v[48:49], v[164:165], 0, v[48:49]
	s_waitcnt lgkmcnt(0)
	v_pk_fma_f32 v[40:41], v[40:41], v[50:51], v[120:121] op_sel_hi:[1,0,1]
	v_pk_fma_f32 v[46:47], v[46:47], v[50:51], v[126:127] op_sel_hi:[1,0,1]
	v_pk_fma_f32 v[44:45], v[44:45], v[50:51], v[124:125] op_sel_hi:[1,0,1]
	v_pk_fma_f32 v[42:43], v[42:43], v[50:51], v[122:123] op_sel_hi:[1,0,1]
	v_max_f32_e32 v40, 0, v40
	v_max_f32_e32 v41, 0, v41
	v_max_f32_e32 v44, 0, v44
	v_max_f32_e32 v45, 0, v45
	v_pk_mul_f32 v[52:53], v[40:41], v[40:41]
	v_max_f32_e32 v40, 0, v46
	v_max_f32_e32 v42, 0, v42
	v_max_f32_e32 v41, 0, v47
	v_max_f32_e32 v43, 0, v43
	v_pk_mul_f32 v[44:45], v[44:45], v[44:45]
	v_pk_mul_f32 v[46:47], v[40:41], v[40:41]
	v_pk_mul_f32 v[54:55], v[42:43], v[42:43]
	v_pk_fma_f32 v[32:33], v[32:33], v[50:51], v[112:113] op_sel_hi:[1,0,1]
	v_cvt_pk_bf16_f32 v40, v44, v45
	v_cvt_pk_bf16_f32 v41, v46, v47
	v_cvt_pk_bf16_f32 v42, v52, v53
	v_cvt_pk_bf16_f32 v43, v54, v55
	v_pk_fma_f32 v[38:39], v[38:39], v[50:51], v[118:119] op_sel_hi:[1,0,1]
	v_pk_fma_f32 v[36:37], v[36:37], v[50:51], v[116:117] op_sel_hi:[1,0,1]
	v_pk_fma_f32 v[34:35], v[34:35], v[50:51], v[114:115] op_sel_hi:[1,0,1]
	v_max_f32_e32 v32, 0, v32
	v_max_f32_e32 v33, 0, v33
	global_store_dwordx4 v[48:49], v[40:43], off
	v_max_f32_e32 v36, 0, v36
	v_max_f32_e32 v37, 0, v37
	v_pk_mul_f32 v[40:41], v[32:33], v[32:33]
	v_max_f32_e32 v32, 0, v38
	v_max_f32_e32 v34, 0, v34
	v_max_f32_e32 v33, 0, v39
	v_max_f32_e32 v35, 0, v35
	v_pk_mul_f32 v[36:37], v[36:37], v[36:37]
	v_pk_mul_f32 v[38:39], v[32:33], v[32:33]
	v_pk_mul_f32 v[42:43], v[34:35], v[34:35]
	v_cvt_pk_bf16_f32 v32, v36, v37
	v_cvt_pk_bf16_f32 v33, v38, v39
	v_cvt_pk_bf16_f32 v34, v40, v41
	v_cvt_pk_bf16_f32 v35, v42, v43
	global_store_dwordx4 v[48:49], v[32:35], off offset:256
	s_nop 1
	v_add_u32_e32 v32, 0xa0, v166
	v_lshl_add_u32 v33, v32, 2, s15
	ds_read_b32 v34, v33
	v_ashrrev_i32_e32 v33, 31, v32
	v_lshlrev_b64 v[32:33], 13, v[32:33]
	v_lshl_add_u64 v[32:33], v[164:165], 0, v[32:33]
	s_waitcnt lgkmcnt(0)
	v_pk_fma_f32 v[24:25], v[24:25], v[34:35], v[120:121] op_sel_hi:[1,0,1]
	v_pk_fma_f32 v[30:31], v[30:31], v[34:35], v[126:127] op_sel_hi:[1,0,1]
	v_pk_fma_f32 v[28:29], v[28:29], v[34:35], v[124:125] op_sel_hi:[1,0,1]
	v_pk_fma_f32 v[26:27], v[26:27], v[34:35], v[122:123] op_sel_hi:[1,0,1]
	v_max_f32_e32 v24, 0, v24
	v_max_f32_e32 v25, 0, v25
	v_max_f32_e32 v28, 0, v28
	v_max_f32_e32 v29, 0, v29
	v_pk_mul_f32 v[36:37], v[24:25], v[24:25]
	v_max_f32_e32 v24, 0, v30
	v_max_f32_e32 v26, 0, v26
	v_max_f32_e32 v25, 0, v31
	v_max_f32_e32 v27, 0, v27
	v_pk_mul_f32 v[28:29], v[28:29], v[28:29]
	v_pk_mul_f32 v[30:31], v[24:25], v[24:25]
	v_pk_mul_f32 v[38:39], v[26:27], v[26:27]
	v_pk_fma_f32 v[16:17], v[16:17], v[34:35], v[112:113] op_sel_hi:[1,0,1]
	v_cvt_pk_bf16_f32 v24, v28, v29
	v_cvt_pk_bf16_f32 v25, v30, v31
	v_cvt_pk_bf16_f32 v26, v36, v37
	v_cvt_pk_bf16_f32 v27, v38, v39
	v_pk_fma_f32 v[22:23], v[22:23], v[34:35], v[118:119] op_sel_hi:[1,0,1]
	v_pk_fma_f32 v[20:21], v[20:21], v[34:35], v[116:117] op_sel_hi:[1,0,1]
	v_pk_fma_f32 v[18:19], v[18:19], v[34:35], v[114:115] op_sel_hi:[1,0,1]
	v_max_f32_e32 v16, 0, v16
	v_max_f32_e32 v17, 0, v17
	global_store_dwordx4 v[32:33], v[24:27], off
	v_max_f32_e32 v20, 0, v20
	v_max_f32_e32 v21, 0, v21
	v_pk_mul_f32 v[24:25], v[16:17], v[16:17]
	v_max_f32_e32 v16, 0, v22
	v_max_f32_e32 v18, 0, v18
	v_max_f32_e32 v17, 0, v23
	v_max_f32_e32 v19, 0, v19
	v_pk_mul_f32 v[20:21], v[20:21], v[20:21]
	v_pk_mul_f32 v[22:23], v[16:17], v[16:17]
	v_pk_mul_f32 v[26:27], v[18:19], v[18:19]
	v_cvt_pk_bf16_f32 v16, v20, v21
	v_cvt_pk_bf16_f32 v17, v22, v23
	v_cvt_pk_bf16_f32 v18, v24, v25
	v_cvt_pk_bf16_f32 v19, v26, v27
	global_store_dwordx4 v[32:33], v[16:19], off offset:256
	s_nop 1
	v_add_u32_e32 v16, 0xb0, v166
	v_lshl_add_u32 v17, v16, 2, s15
	ds_read_b32 v18, v17
	v_ashrrev_i32_e32 v17, 31, v16
	v_lshlrev_b64 v[16:17], 13, v[16:17]
	v_lshl_add_u64 v[16:17], v[164:165], 0, v[16:17]
	s_waitcnt lgkmcnt(0)
	v_pk_fma_f32 v[8:9], v[8:9], v[18:19], v[120:121] op_sel_hi:[1,0,1]
	v_pk_fma_f32 v[14:15], v[14:15], v[18:19], v[126:127] op_sel_hi:[1,0,1]
	v_pk_fma_f32 v[12:13], v[12:13], v[18:19], v[124:125] op_sel_hi:[1,0,1]
	v_pk_fma_f32 v[10:11], v[10:11], v[18:19], v[122:123] op_sel_hi:[1,0,1]
	v_max_f32_e32 v8, 0, v8
	v_max_f32_e32 v9, 0, v9
	v_max_f32_e32 v12, 0, v12
	v_max_f32_e32 v13, 0, v13
	v_pk_mul_f32 v[20:21], v[8:9], v[8:9]
	v_max_f32_e32 v8, 0, v14
	v_max_f32_e32 v10, 0, v10
	v_max_f32_e32 v9, 0, v15
	v_max_f32_e32 v11, 0, v11
	v_pk_mul_f32 v[12:13], v[12:13], v[12:13]
	v_pk_mul_f32 v[14:15], v[8:9], v[8:9]
	v_pk_mul_f32 v[22:23], v[10:11], v[10:11]
	v_pk_fma_f32 v[0:1], v[0:1], v[18:19], v[112:113] op_sel_hi:[1,0,1]
	v_cvt_pk_bf16_f32 v8, v12, v13
	v_cvt_pk_bf16_f32 v9, v14, v15
	v_cvt_pk_bf16_f32 v10, v20, v21
	v_cvt_pk_bf16_f32 v11, v22, v23
	v_pk_fma_f32 v[6:7], v[6:7], v[18:19], v[118:119] op_sel_hi:[1,0,1]
	v_pk_fma_f32 v[4:5], v[4:5], v[18:19], v[116:117] op_sel_hi:[1,0,1]
	v_pk_fma_f32 v[2:3], v[2:3], v[18:19], v[114:115] op_sel_hi:[1,0,1]
	v_max_f32_e32 v0, 0, v0
	v_max_f32_e32 v1, 0, v1
	global_store_dwordx4 v[16:17], v[8:11], off
	v_max_f32_e32 v4, 0, v4
	v_max_f32_e32 v5, 0, v5
	v_pk_mul_f32 v[8:9], v[0:1], v[0:1]
	v_max_f32_e32 v0, 0, v6
	v_max_f32_e32 v2, 0, v2
	v_max_f32_e32 v1, 0, v7
	v_max_f32_e32 v3, 0, v3
	v_pk_mul_f32 v[4:5], v[4:5], v[4:5]
	v_pk_mul_f32 v[6:7], v[0:1], v[0:1]
	v_pk_mul_f32 v[10:11], v[2:3], v[2:3]
	v_cvt_pk_bf16_f32 v0, v4, v5
	v_cvt_pk_bf16_f32 v1, v6, v7
	v_cvt_pk_bf16_f32 v2, v8, v9
	v_cvt_pk_bf16_f32 v3, v10, v11
	global_store_dwordx4 v[16:17], v[0:3], off offset:256
	s_cbranch_vccnz .LBB0_555
	s_andn2_b64 vcc, exec, s[10:11]
	s_cbranch_vccnz .LBB0_554
	s_barrier
	s_branch .LBB0_554
